# first seam uses the XCD barrier; scan deferred-conversion redundant waits removed; SwiGLU rstd cache; attention softmax/PV interleave
# speedup vs baseline: 1.0432x; 1.0171x over previous
; #define LAS __attribute__((address_space(3)))
; __device__ __forceinline__ unsigned pk2(float lo, float hi) { f32x2 v = {lo, hi}; bf16x2_t b = __builtin_convertvector(v, bf16x2_t); return __builtin_bit_cast(unsigned, b); }
; __device__ __forceinline__ void transpose_store(int K, int N, bf16* WT, int mode, LAS float* scr, int item, int lane, const float (&tv)[32]) {
;     const int nblk = N / 32, kb = item / nblk, nb = item % nblk, k0 = 64 * kb, n0 = 32 * nb;
;     int drow0 = n0; if (mode) drow0 = 256 * (n0 >> 7) + (n0 & 127) + (mode == 2 ? 128 : 0);
; #pragma unroll
;     for (int i = 0; i < 32; ++i) scr[(2 * i + (lane >> 5)) * 33 + (lane & 31)] = tv[i];
;     asm volatile("s_waitcnt lgkmcnt(0)" ::: "memory");
;     const int c = lane & 7;
; #pragma unroll
;     for (int j = 0; j < 4; ++j) { const int n = (lane >> 3) + 8 * j; const LAS float* sp = scr + (8 * c) * 33 + n;
;         u32x4 o; o.x = pk2(sp[0 * 33], sp[1 * 33]); o.y = pk2(sp[2 * 33], sp[3 * 33]); o.z = pk2(sp[4 * 33], sp[5 * 33]); o.w = pk2(sp[6 * 33], sp[7 * 33]);
;         *(u32x4*)(WT + (size_t)(drow0 + n) * K + k0 + 8 * c) = o; }
;     asm volatile("s_waitcnt lgkmcnt(0)" ::: "memory");
.LBB0_262:
	s_sext_i32_i16 s89, s33
	v_cvt_f32_i32_e32 v62, s89
	s_sext_i32_i16 s88, s31
	v_cvt_f32_i32_e32 v0, s88
	s_xor_b32 s93, s88, s89
	v_rcp_iflag_f32_e32 v63, v62
	s_ashr_i32 s93, s93, 30
	s_or_b32 s93, s93, 1
	v_mul_f32_e32 v63, v0, v63
	v_trunc_f32_e32 v63, v63
	v_fma_f32 v0, -v63, v62, v0
	v_cvt_i32_f32_e32 v63, v63
	v_cmp_ge_f32_e64 s[88:89], |v0|, |v62|
	s_and_b64 s[88:89], s[88:89], exec
	s_cselect_b32 s88, s93, 0
	v_readfirstlane_b32 s89, v63
	s_add_i32 s88, s89, s88
	s_sext_i32_i16 s89, s88
	s_mul_i32 s88, s88, s33
	s_sub_i32 s31, s31, s88
	s_sext_i32_i16 s31, s31
	s_lshl_b32 s33, s31, 5
	s_lshl_b32 s31, s31, 6
	v_add_u32_e32 v0, v183, v189
	s_and_b32 s31, s31, 0xffffff00
	s_and_b32 s88, s33, 0x60
	v_add_u32_e32 v62, 0x400, v0
	s_cmp_eq_u32 s39, 2
	ds_write2_b32 v0, v2, v3 offset1:66
	ds_write2_b32 v0, v4, v5 offset0:132 offset1:198
	ds_write2_b32 v62, v6, v7 offset0:8 offset1:74
	ds_write2_b32 v62, v8, v9 offset0:140 offset1:206
	v_add_u32_e32 v62, 0x800, v0
	s_cselect_b32 s93, 0x80, 0
	ds_write2_b32 v62, v10, v11 offset0:16 offset1:82
	ds_write2_b32 v62, v12, v13 offset0:148 offset1:214
	v_add_u32_e32 v62, 0xc00, v0
	s_or_b32 s88, s88, s93
	ds_write2_b32 v62, v14, v15 offset0:24 offset1:90
	ds_write2_b32 v62, v16, v17 offset0:156 offset1:222
	v_add_u32_e32 v62, 0x1000, v0
	s_or_b32 s31, s88, s31
	ds_write2_b32 v62, v18, v19 offset0:32 offset1:98
	ds_write2_b32 v62, v20, v21 offset0:164 offset1:230
	v_add_u32_e32 v62, 0x1400, v0
	s_lshl_b32 s88, s89, 6
	ds_write2_b32 v62, v22, v23 offset0:40 offset1:106
	ds_write2_b32 v62, v24, v25 offset0:172 offset1:238
	v_add_u32_e32 v62, 0x1800, v0
	v_add_u32_e32 v0, 0x1c00, v0
	s_cmp_eq_u32 s39, 0
	ds_write2_b32 v62, v26, v27 offset0:48 offset1:114
	ds_write2_b32 v62, v28, v29 offset0:180 offset1:246
	ds_write2_b32 v0, v30, v31 offset0:56 offset1:122
	ds_write2_b32 v0, v32, v33 offset0:188 offset1:254
	s_cselect_b32 s31, s33, s31
	s_ashr_i32 s89, s88, 31
	s_waitcnt lgkmcnt(0)
	s_lshl_b64 s[88:89], s[88:89], 1
	s_add_u32 s20, s20, s88
	ds_read2_b32 v[68:69], v191 offset0:33 offset1:41
	ds_read2_b32 v[70:71], v191 offset1:8
	s_addc_u32 s21, s21, s89
	v_lshlrev_b32_e32 v0, 1, v130
	v_lshl_add_u64 v[66:67], s[20:21], 0, v[0:1]
	ds_read2_b32 v[72:73], v191 offset0:66 offset1:74
	ds_read2_b32 v[74:75], v191 offset0:99 offset1:107
	ds_read2_b32 v[76:77], v191 offset0:132 offset1:140
	ds_read2_b32 v[78:79], v191 offset0:165 offset1:173
	ds_read2_b32 v[80:81], v191 offset0:198 offset1:206
	ds_read2_b32 v[82:83], v191 offset0:231 offset1:239
	v_or_b32_e32 v0, s31, v190
	v_mad_u64_u32 v[84:85], s[20:21], s16, v0, 0
	s_ashr_i32 s20, s31, 31
	s_waitcnt lgkmcnt(6)
	v_cvt_pk_bf16_f32 v62, v70, v68
	v_mul_lo_u32 v68, s17, v0
	s_mul_i32 s33, s16, s20
	v_add3_u32 v85, v85, s33, v68
	s_waitcnt lgkmcnt(4)
	v_cvt_pk_bf16_f32 v63, v72, v74
	s_waitcnt lgkmcnt(2)
	v_cvt_pk_bf16_f32 v64, v76, v78
	s_waitcnt lgkmcnt(0)
	v_cvt_pk_bf16_f32 v65, v80, v82
	v_lshl_add_u64 v[84:85], v[84:85], 1, v[66:67]
	v_or_b32_e32 v0, s31, v192
	global_store_dwordx4 v[84:85], v[62:65], off
	v_mul_lo_u32 v70, s17, v0
	v_readlane_b32 s88, v254, 55
	v_cvt_pk_bf16_f32 v62, v71, v69
	v_mad_u64_u32 v[68:69], s[20:21], s16, v0, 0
	v_add3_u32 v69, v69, s33, v70
	v_cvt_pk_bf16_f32 v63, v73, v75
	v_cvt_pk_bf16_f32 v64, v77, v79
	v_cvt_pk_bf16_f32 v65, v81, v83
	v_lshl_add_u64 v[68:69], v[68:69], 1, v[66:67]
	global_store_dwordx4 v[68:69], v[62:65], off
	ds_read2_b32 v[68:69], v191 offset0:16 offset1:24
	ds_read2_b32 v[70:71], v191 offset0:49 offset1:57
	ds_read2_b32 v[72:73], v191 offset0:82 offset1:90
	ds_read2_b32 v[74:75], v191 offset0:115 offset1:123
	ds_read2_b32 v[76:77], v191 offset0:148 offset1:156
	ds_read2_b32 v[78:79], v191 offset0:181 offset1:189
	ds_read2_b32 v[80:81], v191 offset0:214 offset1:222
	ds_read2_b32 v[82:83], v191 offset0:247 offset1:255
	v_or_b32_e32 v0, s31, v193
	s_waitcnt lgkmcnt(6)
	v_cvt_pk_bf16_f32 v62, v68, v70
	v_mul_lo_u32 v68, s17, v0
	v_mad_u64_u32 v[84:85], s[20:21], s16, v0, 0
	v_add3_u32 v85, v85, s33, v68
	s_waitcnt lgkmcnt(4)
	v_cvt_pk_bf16_f32 v63, v72, v74
	s_waitcnt lgkmcnt(2)
	v_cvt_pk_bf16_f32 v64, v76, v78
	s_waitcnt lgkmcnt(0)
	v_cvt_pk_bf16_f32 v65, v80, v82
	v_lshl_add_u64 v[84:85], v[84:85], 1, v[66:67]
	v_or_b32_e32 v0, s31, v194
	global_store_dwordx4 v[84:85], v[62:65], off
	v_mul_lo_u32 v70, s17, v0
	s_movk_i32 s39, 0x5000
	v_cvt_pk_bf16_f32 v62, v69, v71
	v_mad_u64_u32 v[68:69], s[16:17], s16, v0, 0
	v_add3_u32 v69, v69, s33, v70
	v_cvt_pk_bf16_f32 v63, v73, v75
	v_cvt_pk_bf16_f32 v64, v77, v79
	v_cvt_pk_bf16_f32 v65, v81, v83
	v_lshl_add_u64 v[66:67], v[68:69], 1, v[66:67]
	global_store_dwordx4 v[66:67], v[62:65], off
	s_waitcnt lgkmcnt(0)
	v_readlane_b32 s89, v254, 56

; __device__ __forceinline__ void transpose_load(const float* W, int K, int N, int item, int lane, float (&tv)[32]) {
;     const int nblk = N / 32, kb = item / nblk, nb = item % nblk, k0 = 64 * kb, n0 = 32 * nb;
; #pragma unroll
;     for (int i = 0; i < 32; ++i) tv[i] = W[(size_t)(k0 + 2 * i + (lane >> 5)) * N + n0 + (lane & 31)];
; }
.LBB0_282:
	s_lshr_b32 s23, s30, 5
	v_cvt_f32_i32_e32 v2, s23
	s_sext_i32_i16 s20, s31
	v_cvt_f32_i32_e32 v0, s20
	s_ashr_i32 s21, s20, 30
	v_rcp_iflag_f32_e32 v3, v2
	s_or_b32 s33, s21, 1
	v_mul_f32_e32 v3, v0, v3
	v_trunc_f32_e32 v3, v3
	v_fma_f32 v0, -v3, v2, v0
	v_cvt_i32_f32_e32 v3, v3
	v_cmp_ge_f32_e64 s[20:21], |v0|, v2
	s_and_b64 s[20:21], s[20:21], exec
	s_cselect_b32 s20, s33, 0
	v_readfirstlane_b32 s21, v3
	s_add_i32 s20, s21, s20
	s_sext_i32_i16 s21, s20
	s_mul_i32 s20, s20, s23
	s_sub_i32 s20, s31, s20
	s_sext_i32_i16 s20, s20
	s_lshl_b32 s20, s20, 5
	v_lshl_or_b32 v64, s21, 6, v131
	s_ashr_i32 s21, s20, 31
	s_lshl_b64 s[20:21], s[20:21], 2
	s_waitcnt lgkmcnt(0)
	s_add_u32 s16, s16, s20
	s_addc_u32 s17, s17, s21
	v_lshlrev_b32_e32 v0, 2, v128
	v_lshl_add_u64 v[62:63], s[16:17], 0, v[0:1]
	v_or_b32_e32 v0, 2, v64
	v_mul_hi_i32_i24_e32 v3, s30, v64
	v_mul_i32_i24_e32 v2, s30, v64
	v_mul_hi_i32_i24_e32 v5, s30, v0
	v_mul_i32_i24_e32 v4, s30, v0
	v_lshl_add_u64 v[2:3], v[2:3], 2, v[62:63]
	v_lshl_add_u64 v[4:5], v[4:5], 2, v[62:63]
	v_or_b32_e32 v0, 4, v64
	global_load_dword v2, v[2:3], off
	s_nop 0
	global_load_dword v3, v[4:5], off
	v_mul_hi_i32_i24_e32 v5, s30, v0
	v_mul_i32_i24_e32 v4, s30, v0
	v_or_b32_e32 v0, 6, v64
	v_mul_hi_i32_i24_e32 v7, s30, v0
	v_mul_i32_i24_e32 v6, s30, v0
	v_lshl_add_u64 v[4:5], v[4:5], 2, v[62:63]
	v_lshl_add_u64 v[6:7], v[6:7], 2, v[62:63]
	v_or_b32_e32 v0, 8, v64
	global_load_dword v4, v[4:5], off
	s_nop 0
	global_load_dword v5, v[6:7], off
	v_mul_hi_i32_i24_e32 v7, s30, v0
	v_mul_i32_i24_e32 v6, s30, v0
	v_or_b32_e32 v0, 10, v64
	v_mul_hi_i32_i24_e32 v9, s30, v0
	v_mul_i32_i24_e32 v8, s30, v0
	v_lshl_add_u64 v[6:7], v[6:7], 2, v[62:63]
	v_lshl_add_u64 v[8:9], v[8:9], 2, v[62:63]
	v_or_b32_e32 v0, 12, v64
	global_load_dword v6, v[6:7], off
	s_nop 0
	global_load_dword v7, v[8:9], off
	v_mul_hi_i32_i24_e32 v9, s30, v0
	v_mul_i32_i24_e32 v8, s30, v0
	v_or_b32_e32 v0, 14, v64
	v_mul_hi_i32_i24_e32 v11, s30, v0
	v_mul_i32_i24_e32 v10, s30, v0
	v_lshl_add_u64 v[8:9], v[8:9], 2, v[62:63]
	v_lshl_add_u64 v[10:11], v[10:11], 2, v[62:63]
	v_or_b32_e32 v0, 16, v64
	global_load_dword v8, v[8:9], off
	s_nop 0
	global_load_dword v9, v[10:11], off
	v_mul_hi_i32_i24_e32 v11, s30, v0
	v_mul_i32_i24_e32 v10, s30, v0
	v_or_b32_e32 v0, 18, v64
	v_mul_hi_i32_i24_e32 v13, s30, v0
	v_mul_i32_i24_e32 v12, s30, v0
	v_lshl_add_u64 v[10:11], v[10:11], 2, v[62:63]
	v_lshl_add_u64 v[12:13], v[12:13], 2, v[62:63]
	v_or_b32_e32 v0, 20, v64
	global_load_dword v10, v[10:11], off
	s_nop 0
	global_load_dword v11, v[12:13], off
	v_mul_hi_i32_i24_e32 v13, s30, v0
	v_mul_i32_i24_e32 v12, s30, v0
	v_or_b32_e32 v0, 22, v64
	v_mul_hi_i32_i24_e32 v15, s30, v0
	v_mul_i32_i24_e32 v14, s30, v0
	v_lshl_add_u64 v[12:13], v[12:13], 2, v[62:63]
	v_lshl_add_u64 v[14:15], v[14:15], 2, v[62:63]
	v_or_b32_e32 v0, 24, v64
	global_load_dword v12, v[12:13], off
	s_nop 0
	global_load_dword v13, v[14:15], off
	v_mul_hi_i32_i24_e32 v15, s30, v0
	v_mul_i32_i24_e32 v14, s30, v0
	v_or_b32_e32 v0, 26, v64
	v_mul_hi_i32_i24_e32 v17, s30, v0
	v_mul_i32_i24_e32 v16, s30, v0
	v_lshl_add_u64 v[14:15], v[14:15], 2, v[62:63]
	v_lshl_add_u64 v[16:17], v[16:17], 2, v[62:63]
	v_or_b32_e32 v0, 28, v64
	global_load_dword v14, v[14:15], off
	s_nop 0
	global_load_dword v15, v[16:17], off
	v_mul_hi_i32_i24_e32 v17, s30, v0
	v_mul_i32_i24_e32 v16, s30, v0
	v_or_b32_e32 v0, 30, v64
	v_mul_hi_i32_i24_e32 v19, s30, v0
	v_mul_i32_i24_e32 v18, s30, v0
	v_lshl_add_u64 v[16:17], v[16:17], 2, v[62:63]
	v_lshl_add_u64 v[18:19], v[18:19], 2, v[62:63]
	v_or_b32_e32 v0, 32, v64
	global_load_dword v16, v[16:17], off
	s_nop 0
	global_load_dword v17, v[18:19], off
	v_mul_hi_i32_i24_e32 v19, s30, v0
	v_mul_i32_i24_e32 v18, s30, v0
	v_or_b32_e32 v0, 34, v64
	v_mul_hi_i32_i24_e32 v21, s30, v0
	v_mul_i32_i24_e32 v20, s30, v0
	v_lshl_add_u64 v[18:19], v[18:19], 2, v[62:63]
	v_lshl_add_u64 v[20:21], v[20:21], 2, v[62:63]
	v_or_b32_e32 v0, 36, v64
	global_load_dword v18, v[18:19], off
	s_nop 0
	global_load_dword v19, v[20:21], off
	v_mul_hi_i32_i24_e32 v21, s30, v0
	v_mul_i32_i24_e32 v20, s30, v0
	v_or_b32_e32 v0, 38, v64
	v_mul_hi_i32_i24_e32 v23, s30, v0
	v_mul_i32_i24_e32 v22, s30, v0
	v_lshl_add_u64 v[20:21], v[20:21], 2, v[62:63]
	v_lshl_add_u64 v[22:23], v[22:23], 2, v[62:63]
	v_or_b32_e32 v0, 40, v64
	global_load_dword v20, v[20:21], off
	s_nop 0
	global_load_dword v21, v[22:23], off
	v_mul_hi_i32_i24_e32 v23, s30, v0
	v_mul_i32_i24_e32 v22, s30, v0
	v_or_b32_e32 v0, 42, v64
	v_mul_hi_i32_i24_e32 v25, s30, v0
	v_mul_i32_i24_e32 v24, s30, v0
	v_lshl_add_u64 v[22:23], v[22:23], 2, v[62:63]
	v_lshl_add_u64 v[24:25], v[24:25], 2, v[62:63]
	v_or_b32_e32 v0, 44, v64
	global_load_dword v22, v[22:23], off
	s_nop 0
	global_load_dword v23, v[24:25], off
	v_mul_hi_i32_i24_e32 v25, s30, v0
	v_mul_i32_i24_e32 v24, s30, v0
	v_or_b32_e32 v0, 46, v64
	v_mul_hi_i32_i24_e32 v27, s30, v0
	v_mul_i32_i24_e32 v26, s30, v0
	v_lshl_add_u64 v[24:25], v[24:25], 2, v[62:63]
	v_lshl_add_u64 v[26:27], v[26:27], 2, v[62:63]
	v_or_b32_e32 v0, 48, v64
	global_load_dword v24, v[24:25], off
	s_nop 0
	global_load_dword v25, v[26:27], off
	v_mul_hi_i32_i24_e32 v27, s30, v0
	v_mul_i32_i24_e32 v26, s30, v0
	v_or_b32_e32 v0, 50, v64
	v_mul_hi_i32_i24_e32 v29, s30, v0
	v_mul_i32_i24_e32 v28, s30, v0
	v_lshl_add_u64 v[26:27], v[26:27], 2, v[62:63]
	v_lshl_add_u64 v[28:29], v[28:29], 2, v[62:63]
	v_or_b32_e32 v0, 52, v64
	global_load_dword v26, v[26:27], off
	s_nop 0
	global_load_dword v27, v[28:29], off
	v_mul_hi_i32_i24_e32 v29, s30, v0
	v_mul_i32_i24_e32 v28, s30, v0
	v_or_b32_e32 v0, 54, v64
	v_mul_hi_i32_i24_e32 v31, s30, v0
	v_mul_i32_i24_e32 v30, s30, v0
	v_lshl_add_u64 v[28:29], v[28:29], 2, v[62:63]
	v_lshl_add_u64 v[30:31], v[30:31], 2, v[62:63]
	v_or_b32_e32 v0, 56, v64
	global_load_dword v28, v[28:29], off
	s_nop 0
	global_load_dword v29, v[30:31], off
	v_mul_hi_i32_i24_e32 v31, s30, v0
	v_mul_i32_i24_e32 v30, s30, v0
	v_or_b32_e32 v0, 58, v64
	v_mul_hi_i32_i24_e32 v33, s30, v0
	v_mul_i32_i24_e32 v32, s30, v0
	v_lshl_add_u64 v[30:31], v[30:31], 2, v[62:63]
	v_lshl_add_u64 v[32:33], v[32:33], 2, v[62:63]
	v_or_b32_e32 v0, 60, v64
	global_load_dword v30, v[30:31], off
	s_nop 0
	global_load_dword v31, v[32:33], off
	v_mul_hi_i32_i24_e32 v33, s30, v0
	v_mul_i32_i24_e32 v32, s30, v0
	v_or_b32_e32 v0, 62, v64
	v_mul_hi_i32_i24_e32 v65, s30, v0
	v_mul_i32_i24_e32 v64, s30, v0
	v_lshl_add_u64 v[32:33], v[32:33], 2, v[62:63]
	v_lshl_add_u64 v[62:63], v[64:65], 2, v[62:63]
	global_load_dword v32, v[32:33], off
	s_nop 0
	global_load_dword v33, v[62:63], off

; __device__ __forceinline__ void xcd_barrier(const XcdBarrier& b) {
;     asm volatile("s_waitcnt vmcnt(0)" ::: "memory");
;     __syncthreads();
;     if (threadIdx.x == 0) {
;         unsigned* bar = b.bar;
;         __builtin_amdgcn_s_waitcnt(0);
;         unsigned nloc = b.st[0], nx = b.st[1];
;         if (nloc == 0u) { xcd_barrier_complete(bar, b.x, nloc, nx); b.st[0] = nloc; b.st[1] = nx; }
; __global__ void __launch_bounds__(NTHR, 2) mega_fwd(Args a) {
;     ...
;         if (ph + 1 < a.ph_hi) {
;             if (ph == a.ph_lo) grid.sync(); else xcd_barrier(xbar);
.LBB0_691:
	s_load_dwordx2 s[4:5], s[0:1], 0x118
	s_add_i32 s22, s73, 1
	v_readlane_b32 s40, v254, 44
	v_readlane_b32 s41, v254, 45
	s_waitcnt lgkmcnt(0)
	s_cmp_ge_i32 s22, s5
	s_cbranch_scc1 .LBB0_10
	s_load_dwordx2 s[4:5], s[0:1], 0x118
	s_waitcnt lgkmcnt(0)
	s_cmp_lg_u32 s73, s4
	s_mov_b64 s[4:5], -1
	s_waitcnt vmcnt(0)
	s_waitcnt vmcnt(0)
	s_barrier
	s_mov_b64 s[4:5], exec
	v_readlane_b32 s6, v252, 2
	v_readlane_b32 s7, v252, 3
	s_and_b64 s[6:7], s[4:5], s[6:7]
	s_mov_b64 exec, s[6:7]
	s_cbranch_execz .LBB0_745
	s_add_i32 s2, 0, 0x20000
	v_mov_b32_e32 v0, s2
	s_waitcnt vmcnt(0) expcnt(0) lgkmcnt(0)
	ds_read_b32 v3, v0
	v_readlane_b32 s6, v254, 35
	s_waitcnt lgkmcnt(0)
	v_cmp_ne_u32_e32 vcc, 0, v3
	v_mov_b32_e32 v0, s6
	ds_read_b32 v2, v0
	s_cbranch_vccnz .LBB0_709
	s_mov_b32 s12, 1
	s_branch .LBB0_697
